# rotary-key fp6 image pass at the start of P12 moved to workgroups 144..176 (the ones with 3 GEMM tiles in P12+P13); others skip it and its flag load
# speedup vs baseline: 1.0061x; 1.0004x over previous
; #define GAS __attribute__((address_space(1)))
; __device__ __forceinline__ void kr6_pass(Frame& F) {
;     if (((const float*)(F.ws + WS_HPAR))[448] == 0.f) return;
;     const bf16* KR = (const bf16*)(F.ws + WS_KR); unsigned char* K6R = (unsigned char*)(F.ws + WS_K6R);
;     for (int r = F.vcu * (NWAVES * 64) + F.tid; r < MR; r += F.G * (NWAVES * 64)) {
;         const GAS v4u* rp = (const GAS v4u*)(KR + (size_t)r * 32);
;         v4u w[4] = {rp[0], rp[1], rp[2], rp[3]};
.LBB0_137:
	s_mov_b64 s[2:3], 0
	s_cbranch_execz .LBB0_109
	v_readlane_b32 s0, v243, 19
	s_sub_i32 s0, s0, 0x90
	s_cmp_lt_u32 s0, 33
	s_cbranch_scc0 .LBB0_143
	global_load_dword v0, v187, s[80:81] offset:1792
	s_waitcnt vmcnt(0)
	v_cmp_eq_f32_e32 vcc, 0, v0
	s_cbranch_vccnz .LBB0_143
	v_readlane_b32 s0, v243, 19
	s_sub_i32 s0, s0, 0x90
	s_nop 1
	v_lshl_add_u32 v24, s0, 9, v170
	s_movk_i32 s0, 0x4200
	v_cmp_gt_i32_e32 vcc, s0, v24
	s_and_saveexec_b64 s[0:1], vcc
	s_mov_b32 s12, 0xffff0000
	s_movk_i32 s13, 0x7fff
	s_mov_b32 s14, 0x3fc47802
	s_cbranch_execz .LBB0_142
	s_add_u32 s4, s80, 0x6300000
	v_readlane_b32 s6, v243, 18
	v_ashrrev_i32_e32 v25, 31, v24
	s_addc_u32 s5, s81, 0
	s_lshl_b32 s6, s6, 9
	v_lshlrev_b64 v[2:3], 6, v[24:25]
	v_lshl_add_u64 v[2:3], s[80:81], 0, v[2:3]
	s_mov_b64 s[8:9], 0x8300000
	s_ashr_i32 s7, s6, 31
	v_lshlrev_b32_e32 v0, 4, v172
	v_lshlrev_b32_e32 v26, 3, v172
	v_mov_b32_e32 v27, v1
	v_lshl_add_u64 v[28:29], v[2:3], 0, s[8:9]
	s_lshl_b64 s[8:9], s[6:7], 6
	s_mov_b64 s[10:11], 0

;     ...
;     for (int i = F.tid; i < 1024; i += NWAVES * 64) {
;         gl[i] = gw_[i];
; #pragma unroll
;         for (int cnd = 0; cnd < 3; ++cnd) {
;             float sh, sc;
;             if (from_partials) { sh = ada_b[layer * 6144 + offsh + i]; sc = ada_b[layer * 6144 + offsc + i];
;                 float ph[ADA_KS], pc[ADA_KS];
; #pragma unroll
;                 for (int ks = 0; ks < ADA_KS; ++ks) { const float* p = modp + ((size_t)(ks * 2 + layer) * 3 + cnd) * 6144; ph[ks] = p[offsh + i]; pc[ks] = p[offsc + i]; }
; #pragma unroll
;                 for (int ks = 0; ks < ADA_KS; ++ks) { sh += ph[ks]; sc += pc[ks]; } }
;             else { sh = mod[(layer * 3 + cnd) * 6144 + offsh + i]; sc = mod[(layer * 3 + cnd) * 6144 + offsc + i]; }
;             scl[cnd * 1024 + i] = 1.f + sc; shl[cnd * 1024 + i] = sh;
;         }
;     }
.LBB0_153:
	v_lshlrev_b32_e32 v220, 2, v2
	v_lshlrev_b32_e32 v221, 2, v3
	global_load_dword v236, v220, s[4:5]
	global_load_dword v237, v221, s[4:5]
	v_add_u32_e32 v222, s12, v220
	v_add_u32_e32 v223, s12, v221
	global_load_dword v228, v222, s[8:9] offset:-4096
	global_load_dword v229, v223, s[8:9] offset:-4096
	global_load_dword v230, v222, s[8:9]
	global_load_dword v231, v223, s[8:9]
	v_add_u32_e32 v222, s13, v220
	v_add_u32_e32 v223, s13, v221
	global_load_dword v232, v222, s[8:9] offset:-4096
	global_load_dword v233, v223, s[8:9] offset:-4096
	global_load_dword v234, v222, s[8:9]
	global_load_dword v235, v223, s[8:9]
	v_add_u32_e32 v222, s14, v220
	v_add_u32_e32 v223, s14, v221
	global_load_dword v238, v222, s[8:9] offset:-4096
	global_load_dword v239, v223, s[8:9] offset:-4096
	global_load_dword v240, v222, s[8:9]
	global_load_dword v241, v223, s[8:9]
	v_add_u32_e32 v7, -2, v7
	v_add_u32_e32 v224, 0x400, v2
	v_add_u32_e32 v225, 0x400, v3
	v_lshl_add_u32 v226, v224, 2, 0
	v_lshl_add_u32 v227, v225, 2, 0
	v_cmp_eq_u32_e32 vcc, 0, v7
	s_or_b64 s[10:11], vcc, s[10:11]
	s_waitcnt vmcnt(0)
	ds_write2st64_b32 v8, v236, v237 offset1:8
	v_add_f32_e32 v230, 1.0, v230
	v_add_f32_e32 v231, 1.0, v231
	ds_write2st64_b32 v8, v230, v231 offset0:16 offset1:24
	ds_write2st64_b32 v8, v228, v229 offset0:64 offset1:72
	v_add_f32_e32 v234, 1.0, v234
	v_add_f32_e32 v235, 1.0, v235
	ds_write_b32 v226, v234 offset:4096
	ds_write_b32 v227, v235 offset:4096
	ds_write_b32 v226, v232 offset:16384
	ds_write_b32 v227, v233 offset:16384
	v_add_f32_e32 v240, 1.0, v240
	v_add_f32_e32 v241, 1.0, v241
	ds_write_b32 v220, v240 offset:12288
	ds_write_b32 v221, v241 offset:12288
	ds_write_b32 v220, v238 offset:24576
	ds_write_b32 v221, v239 offset:24576
	v_add_u32_e32 v8, 0x1000, v8
	v_mov_b32_e32 v2, v224
	v_mov_b32_e32 v3, v225
	s_andn2_b64 exec, exec, s[10:11]
	s_cbranch_execnz .LBB0_153
	s_nop 0
	s_nop 0
	s_nop 0
	s_nop 0
	s_nop 0
	s_nop 0
	s_nop 0
	s_nop 0
	s_nop 0
	s_nop 0
	s_nop 0
	s_nop 0
	s_nop 0
	s_nop 0
	s_nop 0
	s_nop 0
	s_nop 0
	s_nop 0
	s_nop 0
	s_nop 0
	s_nop 0
	s_nop 0
	s_nop 0
	s_nop 0
	s_nop 0
	s_or_b64 exec, exec, s[10:11]
	v_cmp_ne_u32_e32 vcc, v0, v6
	v_lshl_add_u32 v2, v6, 9, v170
	s_orn2_b64 s[8:9], vcc, exec
